# merge-GEMM epilogue: first two vmcnt(0) drains relaxed to vmcnt(2) so the gate-row refill loads stay in flight
# speedup vs baseline: 1.0009x; 1.0007x over previous
; __device__ __forceinline__ float bflo(unsigned w) { return __uint_as_float(w << 16); }
; __device__ __forceinline__ float bfhi(unsigned w) { return __uint_as_float(w & 0xffff0000u); }
; __device__ __forceinline__ unsigned pk2(float lo, float hi) { unsigned r; asm("v_cvt_pk_bf16_f32 %0, %1, %2" : "=v"(r) : "v"(lo), "v"(hi)); return r; }
;     __device__ __forceinline__ void operator()(const Acc& acc, const Unit& u, int wr, int wc, int fr, int fq) const {
;     ...
;         for (int gidx = 0; gidx < 8; ++gidx) {
;             const int ai = gidx >> 2, m = gidx & 3;
;             if (gidx + 1 < 8) { const int ai2 = (gidx + 1) >> 2, m2 = (gidx + 1) & 3; const size_t row2 = (size_t)(row0 + ai2 * 128 + m2 * 16);
; #pragma unroll
;                 for (int bj = 0; bj < 2; ++bj) pw[(gidx + 1) & 1][bj] = accum ? *(const u32x4*)(mg + row2 * 2048 + col0 + bj * 128) : (u32x4){0u, 0u, 0u, 0u}; }
;             u32x4 gcur[2];
; #pragma unroll
;             for (int bj = 0; bj < 2; ++bj) { gcur[bj] = gw[gidx & 3][bj];
;                 if (gidx < 4) gw[gidx & 3][bj] = *(const u32x4*)(gp + (size_t)(row0 + 128 + m * 16) * 4096 + col0 + bj * 128); }
;             const size_t row = (size_t)(row0 + ai * 128 + m * 16);
; #pragma unroll
;             for (int bj = 0; bj < 2; ++bj) { const u32x4 g4 = gcur[bj], p4 = pw[gidx & 1][bj];
;                 float o[8]; const f32x4 v0 = acc[ai][bj][m][0], v1 = acc[ai][bj][m][1];
;                 o[0] = bflo(g4.x) * v0[0] + bflo(p4.x); o[1] = bfhi(g4.x) * v0[1] + bfhi(p4.x); o[2] = bflo(g4.y) * v0[2] + bflo(p4.y); o[3] = bfhi(g4.y) * v0[3] + bfhi(p4.y);
;                 o[4] = bflo(g4.z) * v1[0] + bflo(p4.z); o[5] = bfhi(g4.z) * v1[1] + bfhi(p4.z); o[6] = bflo(g4.w) * v1[2] + bflo(p4.w); o[7] = bfhi(g4.w) * v1[3] + bfhi(p4.w);
;                 u32x4 w; w.x = pk2(o[0], o[1]); w.y = pk2(o[2], o[3]); w.z = pk2(o[4], o[5]); w.w = pk2(o[6], o[7]);
;                 *(u32x4*)(mg + row * 2048 + col0 + bj * 128) = w; }
.LBB0_52:
	v_add_u32_e32 v220, 0x80, v222
	v_ashrrev_i32_e32 v221, 31, v220
	v_lshlrev_b64 v[128:129], 13, v[220:221]
	v_lshl_add_u64 v[128:129], v[224:225], 0, v[128:129]
	global_load_dwordx4 v[136:139], v[128:129], off
	s_nop 0
	global_load_dwordx4 v[128:131], v[128:129], off offset:256
	s_waitcnt vmcnt(2)
	v_lshlrev_b32_e32 v190, 16, v176
	v_lshlrev_b32_e32 v191, 16, v180
	v_fmac_f32_e32 v191, v124, v190
	v_and_b32_e32 v124, 0xffff0000, v176
	v_and_b32_e32 v176, 0xffff0000, v180
	v_fmac_f32_e32 v176, v125, v124
	v_lshlrev_b32_e32 v124, 16, v177
	v_lshlrev_b32_e32 v125, 16, v181
	v_fmac_f32_e32 v125, v126, v124
	v_and_b32_e32 v124, 0xffff0000, v177
	v_and_b32_e32 v126, 0xffff0000, v181
	v_fmac_f32_e32 v126, v127, v124
	v_lshlrev_b32_e32 v124, 16, v178
	v_lshlrev_b32_e32 v127, 16, v182
	v_fmac_f32_e32 v127, v120, v124
	v_and_b32_e32 v120, 0xffff0000, v178
	v_and_b32_e32 v124, 0xffff0000, v182
	v_fmac_f32_e32 v124, v121, v120
	v_lshlrev_b32_e32 v120, 16, v179
	v_lshlrev_b32_e32 v177, 16, v183
	v_fmac_f32_e32 v177, v122, v120
	v_and_b32_e32 v120, 0xffff0000, v179
	v_and_b32_e32 v178, 0xffff0000, v183
	v_lshl_add_u64 v[188:189], v[218:219], 0, v[232:233]
	v_fmac_f32_e32 v178, v123, v120
	v_cvt_pk_bf16_f32 v120, v191, v176
	v_cvt_pk_bf16_f32 v121, v125, v126
	v_cvt_pk_bf16_f32 v122, v127, v124
	v_cvt_pk_bf16_f32 v123, v177, v178
	global_store_dwordx4 v[188:189], v[120:123], off
	s_and_b64 vcc, exec, s[8:9]
	v_mov_b32_e32 v124, 0
	v_lshlrev_b32_e32 v120, 16, v168
	v_lshlrev_b32_e32 v121, 16, v172
	v_fmac_f32_e32 v121, v116, v120
	v_and_b32_e32 v116, 0xffff0000, v168
	v_and_b32_e32 v120, 0xffff0000, v172
	v_fmac_f32_e32 v120, v117, v116
	v_lshlrev_b32_e32 v116, 16, v169
	v_lshlrev_b32_e32 v117, 16, v173
	v_fmac_f32_e32 v117, v118, v116
	v_and_b32_e32 v116, 0xffff0000, v169
	v_and_b32_e32 v118, 0xffff0000, v173
	v_fmac_f32_e32 v118, v119, v116
	v_lshlrev_b32_e32 v116, 16, v170
	v_lshlrev_b32_e32 v119, 16, v174
	v_fmac_f32_e32 v119, v112, v116
	v_and_b32_e32 v112, 0xffff0000, v170
	v_and_b32_e32 v116, 0xffff0000, v174
	v_fmac_f32_e32 v116, v113, v112
	v_lshlrev_b32_e32 v112, 16, v171
	v_lshlrev_b32_e32 v122, 16, v175
	v_fmac_f32_e32 v122, v114, v112
	v_and_b32_e32 v112, 0xffff0000, v171
	v_and_b32_e32 v123, 0xffff0000, v175
	v_fmac_f32_e32 v123, v115, v112
	v_cvt_pk_bf16_f32 v112, v121, v120
	v_cvt_pk_bf16_f32 v113, v117, v118
	v_cvt_pk_bf16_f32 v114, v119, v116
	v_cvt_pk_bf16_f32 v115, v122, v123
	global_store_dwordx4 v[188:189], v[112:115], off offset:256
	v_mov_b32_e32 v120, 0
	v_mov_b32_e32 v125, 0
	v_lshlrev_b64 v[112:113], 12, v[230:231]
	v_lshl_add_u64 v[168:169], v[218:219], 0, v[112:113]
	v_mov_b32_e32 v126, 0
	v_mov_b32_e32 v127, 0
	s_cbranch_vccnz .LBB0_54
	global_load_dwordx4 v[124:127], v[168:169], off

; __device__ __forceinline__ float bflo(unsigned w) { return __uint_as_float(w << 16); }
; __device__ __forceinline__ float bfhi(unsigned w) { return __uint_as_float(w & 0xffff0000u); }
; __device__ __forceinline__ unsigned pk2(float lo, float hi) { unsigned r; asm("v_cvt_pk_bf16_f32 %0, %1, %2" : "=v"(r) : "v"(lo), "v"(hi)); return r; }
;     __device__ __forceinline__ void operator()(const Acc& acc, const Unit& u, int wr, int wc, int fr, int fq) const {
;     ...
;         for (int gidx = 0; gidx < 8; ++gidx) {
;             const int ai = gidx >> 2, m = gidx & 3;
;             if (gidx + 1 < 8) { const int ai2 = (gidx + 1) >> 2, m2 = (gidx + 1) & 3; const size_t row2 = (size_t)(row0 + ai2 * 128 + m2 * 16);
; #pragma unroll
;                 for (int bj = 0; bj < 2; ++bj) pw[(gidx + 1) & 1][bj] = accum ? *(const u32x4*)(mg + row2 * 2048 + col0 + bj * 128) : (u32x4){0u, 0u, 0u, 0u}; }
;             u32x4 gcur[2];
; #pragma unroll
;             for (int bj = 0; bj < 2; ++bj) { gcur[bj] = gw[gidx & 3][bj];
;                 if (gidx < 4) gw[gidx & 3][bj] = *(const u32x4*)(gp + (size_t)(row0 + 128 + m * 16) * 4096 + col0 + bj * 128); }
;             const size_t row = (size_t)(row0 + ai * 128 + m * 16);
; #pragma unroll
;             for (int bj = 0; bj < 2; ++bj) { const u32x4 g4 = gcur[bj], p4 = pw[gidx & 1][bj];
;                 float o[8]; const f32x4 v0 = acc[ai][bj][m][0], v1 = acc[ai][bj][m][1];
;                 o[0] = bflo(g4.x) * v0[0] + bflo(p4.x); o[1] = bfhi(g4.x) * v0[1] + bfhi(p4.x); o[2] = bflo(g4.y) * v0[2] + bflo(p4.y); o[3] = bfhi(g4.y) * v0[3] + bfhi(p4.y);
;                 o[4] = bflo(g4.z) * v1[0] + bflo(p4.z); o[5] = bfhi(g4.z) * v1[1] + bfhi(p4.z); o[6] = bflo(g4.w) * v1[2] + bflo(p4.w); o[7] = bfhi(g4.w) * v1[3] + bfhi(p4.w);
;                 u32x4 w; w.x = pk2(o[0], o[1]); w.y = pk2(o[2], o[3]); w.z = pk2(o[4], o[5]); w.w = pk2(o[6], o[7]);
;                 *(u32x4*)(mg + row * 2048 + col0 + bj * 128) = w; }
.LBB0_60:
	v_lshlrev_b64 v[96:97], 13, v[222:223]
	v_lshl_add_u64 v[96:97], v[224:225], 0, v[96:97]
	s_mov_b64 s[22:23], 0x140000
	v_lshl_add_u64 v[98:99], v[96:97], 0, s[22:23]
	v_add_co_u32_e32 v96, vcc, 0x140000, v96
	v_lshlrev_b32_e32 v154, 16, v148
	s_nop 0
	v_addc_co_u32_e32 v97, vcc, 0, v97, vcc
	global_load_dwordx4 v[100:103], v[96:97], off
	s_nop 0
	global_load_dwordx4 v[96:99], v[98:99], off offset:256
	s_waitcnt vmcnt(2)
	v_lshlrev_b32_e32 v155, 16, v124
	v_fmac_f32_e32 v155, v92, v154
	v_and_b32_e32 v92, 0xffff0000, v148
	v_and_b32_e32 v124, 0xffff0000, v124
	v_fmac_f32_e32 v124, v93, v92
	v_lshlrev_b32_e32 v92, 16, v149
	v_lshlrev_b32_e32 v93, 16, v125
	v_fmac_f32_e32 v93, v94, v92
	v_and_b32_e32 v92, 0xffff0000, v149
	v_and_b32_e32 v94, 0xffff0000, v125
	v_fmac_f32_e32 v94, v95, v92
	v_lshlrev_b32_e32 v92, 16, v150
	v_lshlrev_b32_e32 v95, 16, v126
	v_fmac_f32_e32 v95, v88, v92
	v_and_b32_e32 v88, 0xffff0000, v150
	v_and_b32_e32 v92, 0xffff0000, v126
	v_fmac_f32_e32 v92, v89, v88
	v_lshlrev_b32_e32 v88, 16, v151
	v_lshlrev_b32_e32 v125, 16, v127
	v_fmac_f32_e32 v125, v90, v88
	v_and_b32_e32 v88, 0xffff0000, v151
	v_and_b32_e32 v126, 0xffff0000, v127
	v_fmac_f32_e32 v126, v91, v88
	v_cvt_pk_bf16_f32 v88, v155, v124
	v_cvt_pk_bf16_f32 v89, v93, v94
	v_cvt_pk_bf16_f32 v90, v95, v92
	v_cvt_pk_bf16_f32 v91, v125, v126
	global_store_dwordx4 v[168:169], v[88:91], off
	s_and_b64 vcc, exec, s[8:9]
	v_mov_b32_e32 v92, 0
	v_lshlrev_b32_e32 v88, 16, v144
	v_lshlrev_b32_e32 v89, 16, v120
	v_fmac_f32_e32 v89, v84, v88
	v_and_b32_e32 v84, 0xffff0000, v144
	v_and_b32_e32 v88, 0xffff0000, v120
	v_fmac_f32_e32 v88, v85, v84
	v_lshlrev_b32_e32 v84, 16, v145
	v_lshlrev_b32_e32 v85, 16, v121
	v_fmac_f32_e32 v85, v86, v84
	v_and_b32_e32 v84, 0xffff0000, v145
	v_and_b32_e32 v86, 0xffff0000, v121
	v_fmac_f32_e32 v86, v87, v84
	v_lshlrev_b32_e32 v84, 16, v146
	v_lshlrev_b32_e32 v87, 16, v122
	v_fmac_f32_e32 v87, v80, v84
	v_and_b32_e32 v80, 0xffff0000, v146
	v_and_b32_e32 v84, 0xffff0000, v122
	v_fmac_f32_e32 v84, v81, v80
	v_lshlrev_b32_e32 v80, 16, v147
	v_lshlrev_b32_e32 v90, 16, v123
	v_fmac_f32_e32 v90, v82, v80
	v_and_b32_e32 v80, 0xffff0000, v147
	v_and_b32_e32 v91, 0xffff0000, v123
	v_fmac_f32_e32 v91, v83, v80
	v_cvt_pk_bf16_f32 v80, v89, v88
	v_cvt_pk_bf16_f32 v81, v85, v86
	v_cvt_pk_bf16_f32 v82, v87, v84
	v_cvt_pk_bf16_f32 v83, v90, v91
	global_store_dwordx4 v[168:169], v[80:83], off offset:256
	v_mov_b32_e32 v88, 0
	v_mov_b32_e32 v93, 0
	v_lshlrev_b64 v[80:81], 12, v[220:221]
	v_lshl_add_u64 v[120:121], v[218:219], 0, v[80:81]
	v_mov_b32_e32 v94, 0
	v_mov_b32_e32 v95, 0
	s_cbranch_vccnz .LBB0_62
	global_load_dwordx4 v[92:95], v[120:121], off
